# grid barrier: dropped the now-unread per-XCD generation atomic on the leader path (on v47)
# speedup vs baseline: 1.0066x; 1.0023x over previous
; __device__ __forceinline__ unsigned xb_ld(unsigned* p)              { return __hip_atomic_load(p, __ATOMIC_RELAXED, __HIP_MEMORY_SCOPE_AGENT); }
; __device__ __forceinline__ unsigned xb_add(unsigned* p, unsigned v) { return __hip_atomic_fetch_add(p, v, __ATOMIC_RELAXED, __HIP_MEMORY_SCOPE_AGENT); }
; #define XB_SPIN(cond, bar) do { unsigned _sp = 0; while (cond) { __builtin_amdgcn_s_sleep(1); \
;     if ((++_sp & 255u) == 0u) { if (xb_ld(&(bar)[XB_TMO])) break; if (_sp > XB_SPIN_CAP) { atomicAdd(&(bar)[XB_TMO], 1u); break; } } } } while (0)
; __device__ __forceinline__ void xcd_barrier(unsigned* bar, volatile LAS unsigned* st, const int wid0) {
;     ...
;         if (old + 1u == (gen + 1u) * nloc) {
;             __builtin_amdgcn_fence(__ATOMIC_RELEASE, "agent");
;             asm volatile("s_waitcnt vmcnt(0)" ::: "memory");
;             const unsigned og = xb_add(&bar[XB_TOP], 1u);
;             const unsigned tg = og / nx;
;             if (og + 1u == (tg + 1u) * nx) xb_add(&bar[XB_TOPGEN], 1u);
;             else XB_SPIN(xb_ld(&bar[XB_TOPGEN]) == tg, bar);
;             __builtin_amdgcn_fence(__ATOMIC_ACQUIRE, "agent");
;             xb_add(&bar[XB_XGEN(x)], 1u);
;             asm volatile("s_waitcnt vmcnt(0)" ::: "memory");
.LBB0_469:
	s_or_b64 exec, exec, s[6:7]
	s_mov_b64 s[6:7], exec
	v_mbcnt_lo_u32_b32 v0, s6, 0
	v_mbcnt_hi_u32_b32 v0, s7, v0
	v_cmp_eq_u32_e32 vcc, 0, v0
	s_waitcnt vmcnt(0)
	buffer_inv sc1
	s_and_saveexec_b64 s[8:9], vcc
	s_cbranch_execz .LBB0_471
	s_bcnt1_i32_b64 s3, s[6:7]
	v_mov_b32_e32 v0, 0x2000
	v_mov_b32_e32 v1, s3
	s_nop 0

; __device__ __forceinline__ unsigned xb_ld(unsigned* p)              { return __hip_atomic_load(p, __ATOMIC_RELAXED, __HIP_MEMORY_SCOPE_AGENT); }
; __device__ __forceinline__ unsigned xb_add(unsigned* p, unsigned v) { return __hip_atomic_fetch_add(p, v, __ATOMIC_RELAXED, __HIP_MEMORY_SCOPE_AGENT); }
; #define XB_SPIN(cond, bar) do { unsigned _sp = 0; while (cond) { __builtin_amdgcn_s_sleep(1); \
;     if ((++_sp & 255u) == 0u) { if (xb_ld(&(bar)[XB_TMO])) break; if (_sp > XB_SPIN_CAP) { atomicAdd(&(bar)[XB_TMO], 1u); break; } } } } while (0)
; __device__ __forceinline__ void xcd_barrier(unsigned* bar, volatile LAS unsigned* st, const int wid0) {
;     ...
;         if (old + 1u == (gen + 1u) * nloc) {
;             __builtin_amdgcn_fence(__ATOMIC_RELEASE, "agent");
;             asm volatile("s_waitcnt vmcnt(0)" ::: "memory");
;             const unsigned og = xb_add(&bar[XB_TOP], 1u);
;             const unsigned tg = og / nx;
;             if (og + 1u == (tg + 1u) * nx) xb_add(&bar[XB_TOPGEN], 1u);
;             else XB_SPIN(xb_ld(&bar[XB_TOPGEN]) == tg, bar);
;             __builtin_amdgcn_fence(__ATOMIC_ACQUIRE, "agent");
;             xb_add(&bar[XB_XGEN(x)], 1u);
;             asm volatile("s_waitcnt vmcnt(0)" ::: "memory");
.LBB0_878:
	s_or_b64 exec, exec, s[8:9]
	s_mov_b64 s[8:9], exec
	v_mbcnt_lo_u32_b32 v0, s8, 0
	v_mbcnt_hi_u32_b32 v0, s9, v0
	v_cmp_eq_u32_e32 vcc, 0, v0
	s_waitcnt vmcnt(0)
	buffer_inv sc1
	s_and_saveexec_b64 s[12:13], vcc
	s_cbranch_execz .LBB0_880
	s_bcnt1_i32_b64 s2, s[8:9]
	v_mov_b32_e32 v0, s2
	v_mov_b32_e32 v1, 0x2000
	s_nop 0

; __device__ __forceinline__ unsigned xb_ld(unsigned* p)              { return __hip_atomic_load(p, __ATOMIC_RELAXED, __HIP_MEMORY_SCOPE_AGENT); }
; __device__ __forceinline__ unsigned xb_add(unsigned* p, unsigned v) { return __hip_atomic_fetch_add(p, v, __ATOMIC_RELAXED, __HIP_MEMORY_SCOPE_AGENT); }
; #define XB_SPIN(cond, bar) do { unsigned _sp = 0; while (cond) { __builtin_amdgcn_s_sleep(1); \
;     if ((++_sp & 255u) == 0u) { if (xb_ld(&(bar)[XB_TMO])) break; if (_sp > XB_SPIN_CAP) { atomicAdd(&(bar)[XB_TMO], 1u); break; } } } } while (0)
; __device__ __forceinline__ void xcd_barrier(unsigned* bar, volatile LAS unsigned* st, const int wid0) {
;     ...
;         if (old + 1u == (gen + 1u) * nloc) {
;             __builtin_amdgcn_fence(__ATOMIC_RELEASE, "agent");
;             asm volatile("s_waitcnt vmcnt(0)" ::: "memory");
;             const unsigned og = xb_add(&bar[XB_TOP], 1u);
;             const unsigned tg = og / nx;
;             if (og + 1u == (tg + 1u) * nx) xb_add(&bar[XB_TOPGEN], 1u);
;             else XB_SPIN(xb_ld(&bar[XB_TOPGEN]) == tg, bar);
;             __builtin_amdgcn_fence(__ATOMIC_ACQUIRE, "agent");
;             xb_add(&bar[XB_XGEN(x)], 1u);
;             asm volatile("s_waitcnt vmcnt(0)" ::: "memory");
.LBB0_1028:
	s_or_b64 exec, exec, s[8:9]
	s_mov_b64 s[8:9], exec
	v_mbcnt_lo_u32_b32 v0, s8, 0
	v_mbcnt_hi_u32_b32 v0, s9, v0
	v_cmp_eq_u32_e32 vcc, 0, v0
	s_waitcnt vmcnt(0)
	buffer_inv sc1
	s_and_saveexec_b64 s[10:11], vcc
	s_cbranch_execz .LBB0_1030
	s_bcnt1_i32_b64 s2, s[8:9]
	v_mov_b32_e32 v0, s2
	v_mov_b32_e32 v1, 0x2000
	s_nop 0

; __device__ __forceinline__ unsigned xb_ld(unsigned* p)              { return __hip_atomic_load(p, __ATOMIC_RELAXED, __HIP_MEMORY_SCOPE_AGENT); }
; __device__ __forceinline__ unsigned xb_add(unsigned* p, unsigned v) { return __hip_atomic_fetch_add(p, v, __ATOMIC_RELAXED, __HIP_MEMORY_SCOPE_AGENT); }
; #define XB_SPIN(cond, bar) do { unsigned _sp = 0; while (cond) { __builtin_amdgcn_s_sleep(1); \
;     if ((++_sp & 255u) == 0u) { if (xb_ld(&(bar)[XB_TMO])) break; if (_sp > XB_SPIN_CAP) { atomicAdd(&(bar)[XB_TMO], 1u); break; } } } } while (0)
; __device__ __forceinline__ void xcd_barrier(unsigned* bar, volatile LAS unsigned* st, const int wid0) {
;     ...
;         if (old + 1u == (gen + 1u) * nloc) {
;             __builtin_amdgcn_fence(__ATOMIC_RELEASE, "agent");
;             asm volatile("s_waitcnt vmcnt(0)" ::: "memory");
;             const unsigned og = xb_add(&bar[XB_TOP], 1u);
;             const unsigned tg = og / nx;
;             if (og + 1u == (tg + 1u) * nx) xb_add(&bar[XB_TOPGEN], 1u);
;             else XB_SPIN(xb_ld(&bar[XB_TOPGEN]) == tg, bar);
;             __builtin_amdgcn_fence(__ATOMIC_ACQUIRE, "agent");
;             xb_add(&bar[XB_XGEN(x)], 1u);
;             asm volatile("s_waitcnt vmcnt(0)" ::: "memory");
.LBB0_1127:
	s_or_b64 exec, exec, s[10:11]
	s_mov_b64 s[10:11], exec
	v_mbcnt_lo_u32_b32 v0, s10, 0
	v_mbcnt_hi_u32_b32 v0, s11, v0
	v_cmp_eq_u32_e32 vcc, 0, v0
	s_waitcnt vmcnt(0)
	buffer_inv sc1
	s_and_saveexec_b64 s[30:31], vcc
	s_cbranch_execz .LBB0_1129
	s_bcnt1_i32_b64 s2, s[10:11]
	v_mov_b32_e32 v0, s2
	v_mov_b32_e32 v1, 0x2000
	s_nop 0
